# layer-0 norm_rows row loop software-pipelined: next row's 12 loads are issued before the current row is reduced/normalised (working copy in renamed registers)
# baseline (speedup 1.0000x reference)
; __device__ __forceinline__ unsigned pk2(float lo, float hi) { f32x2_t v = {lo, hi}; bf16x2_t b = __builtin_convertvector(v, bf16x2_t); return __builtin_bit_cast(unsigned, b); }
; __device__ __forceinline__ void norm_rows(const float* x, const float* g, const float* modl  , int sh_off, int sc_off, bf16_t* h, int gw, int ngw, int lane) {
;     f32x4 gv[4];
; #pragma unroll
;     for (int j = 0; j < 4; ++j) gv[j] = *((const f32x4*)g + lane + 64 * j);
;     for (int row = gw; row < M; row += ngw) {
;         const f32x4* xr = (const f32x4*)(x + (size_t)row * DM) + lane;
;         f32x4 v[4]; float ss = 0.f;
; #pragma unroll
;         for (int j = 0; j < 4; ++j) { v[j] = xr[64 * j]; ss += (v[j].x * v[j].x + v[j].y * v[j].y) + (v[j].z * v[j].z + v[j].w * v[j].w); }
;         const float rstd = 1.0f / sqrtf(wave_sum(ss) * (1.0f / DM) + NORM_EPS);
;         const float* mb = modl + (size_t)(row >> 11) * 6 * DM;
;         unsigned long long* o8 = (unsigned long long*)(h + (size_t)row * DM) + lane;
; #pragma unroll
;         for (int j = 0; j < 4; ++j) {
;             const f32x4 sc = *((const f32x4*)(mb + sc_off) + lane + 64 * j), sh = *((const f32x4*)(mb + sh_off) + lane + 64 * j);
;             const f32x4 y = v[j] * rstd * gv[j] * (sc + 1.0f) + sh;
;             o8[64 * j] = (unsigned long long)pk2(y.x, y.y) | ((unsigned long long)pk2(y.z, y.w) << 32);
;         }
.LBB0_688:
	v_readlane_b32 s0, v255, 50
	v_readlane_b32 s1, v255, 51
	s_andn2_b64 vcc, exec, s[0:1]
	s_cbranch_vccnz .LBB0_692
	s_cmpk_gt_i32 s2, 0x3fff
	s_cbranch_scc1 .LBB0_692
	v_readlane_b32 s4, v254, 2
	v_lshlrev_b32_e32 v64, 4, v16
	v_readlane_b32 s12, v254, 10
	v_readlane_b32 s13, v254, 11
	s_waitcnt lgkmcnt(0)
	s_nop 3
	global_load_dwordx4 v[0:3], v64, s[12:13]
	global_load_dwordx4 v[4:7], v64, s[12:13] offset:1024
	global_load_dwordx4 v[8:11], v64, s[12:13] offset:2048
	global_load_dwordx4 v[12:15], v64, s[12:13] offset:3072
	s_ashr_i32 s3, s2, 31
	s_lshl_b64 s[0:1], s[2:3], 11
	s_add_u32 s0, s86, s0
	v_lshlrev_b32_e32 v18, 3, v16
	v_mov_b32_e32 v19, v65
	s_addc_u32 s1, s87, s1
	v_readlane_b32 s6, v254, 4
	v_readlane_b32 s7, v254, 5
	v_lshl_add_u64 v[20:21], s[0:1], 0, v[18:19]
	s_lshl_b64 s[0:1], s[2:3], 12
	v_readlane_b32 s3, v255, 3
	v_readlane_b32 s5, v254, 3
	v_readlane_b32 s8, v254, 6
	v_readlane_b32 s9, v254, 7
	s_add_u32 s0, s3, s0
	v_readlane_b32 s3, v255, 4
	v_readlane_b32 s6, v255, 11
	s_addc_u32 s1, s3, s1
	v_readlane_b32 s4, v255, 1
	v_readlane_b32 s7, v255, 12
	v_readlane_b32 s8, v255, 46
	v_lshl_add_u64 v[22:23], s[0:1], 0, v[64:65]
	v_lshlrev_b32_e32 v64, 4, v16
	v_readlane_b32 s5, v255, 2
	s_mov_b32 s3, 0xf800000
	v_readlane_b32 s9, v255, 47
	v_readlane_b32 s7, v255, 48
	v_readlane_b32 s10, v254, 8
	v_readlane_b32 s11, v254, 9
	v_readlane_b32 s14, v254, 12
	v_readlane_b32 s15, v254, 13
	v_readlane_b32 s16, v254, 14
	v_readlane_b32 s17, v254, 15
	v_readlane_b32 s18, v254, 16
	v_readlane_b32 s19, v254, 17
	global_load_dwordx4 v[24:27], v[22:23], off offset:-3072
	global_load_dwordx4 v[28:31], v[22:23], off offset:-2048
	global_load_dwordx4 v[32:35], v[22:23], off offset:-1024
	global_load_dwordx4 v[16:19], v[22:23], off
	s_ashr_i32 s0, s2, 11
	s_mul_i32 s0, s0, 6
	s_ashr_i32 s1, s0, 31
	s_lshl_b64 s[0:1], s[0:1], 12
	s_add_u32 s0, s7, s0
	s_addc_u32 s1, s35, s1
	v_lshl_add_u64 v[44:45], s[0:1], 0, v[64:65]
	s_mov_b64 s[0:1], 0x1000
	v_lshl_add_u64 v[46:47], v[44:45], 0, s[0:1]
	s_movk_i32 s0, 0x1000
	v_add_co_u32_e32 v40, vcc, s0, v44
	s_add_i32 s2, s2, s6
	s_nop 0
	v_addc_co_u32_e32 v41, vcc, 0, v45, vcc
	flat_load_dwordx4 v[36:39], v[44:45]
	s_nop 0
	flat_load_dwordx4 v[40:43], v[40:41]
	flat_load_dwordx4 v[100:103], v[46:47] offset:1024
	flat_load_dwordx4 v[104:107], v[44:45] offset:1024
	flat_load_dwordx4 v[108:111], v[46:47] offset:2048
	flat_load_dwordx4 v[112:115], v[44:45] offset:2048
	flat_load_dwordx4 v[116:119], v[46:47] offset:3072
	flat_load_dwordx4 v[120:123], v[44:45] offset:3072
	v_lshl_add_u64 v[22:23], v[22:23], 0, s[8:9]
.LBB0_691:
	s_waitcnt vmcnt(0)
	v_mov_b64_e32 v[124:125], v[16:17]
	v_mov_b64_e32 v[126:127], v[18:19]
	v_mov_b64_e32 v[128:129], v[24:25]
	v_mov_b64_e32 v[130:131], v[26:27]
	v_mov_b64_e32 v[132:133], v[28:29]
	v_mov_b64_e32 v[134:135], v[30:31]
	v_mov_b64_e32 v[136:137], v[32:33]
	v_mov_b64_e32 v[138:139], v[34:35]
	v_mov_b64_e32 v[140:141], v[36:37]
	v_mov_b64_e32 v[142:143], v[38:39]
	v_mov_b64_e32 v[144:145], v[40:41]
	v_mov_b64_e32 v[146:147], v[42:43]
	v_mov_b64_e32 v[148:149], v[100:101]
	v_mov_b64_e32 v[150:151], v[102:103]
	v_mov_b64_e32 v[152:153], v[104:105]
	v_mov_b64_e32 v[154:155], v[106:107]
	v_mov_b64_e32 v[156:157], v[108:109]
	v_mov_b64_e32 v[158:159], v[110:111]
	v_mov_b64_e32 v[160:161], v[112:113]
	v_mov_b64_e32 v[162:163], v[114:115]
	v_mov_b64_e32 v[164:165], v[116:117]
	v_mov_b64_e32 v[166:167], v[118:119]
	v_mov_b64_e32 v[168:169], v[120:121]
	v_mov_b64_e32 v[170:171], v[122:123]
	s_cmpk_gt_i32 s2, 0x3fff
	s_cselect_b32 s98, 1, 0
	s_cbranch_scc1 .Lnr_skip
	global_load_dwordx4 v[24:27], v[22:23], off offset:-3072
	global_load_dwordx4 v[28:31], v[22:23], off offset:-2048
	global_load_dwordx4 v[32:35], v[22:23], off offset:-1024
	global_load_dwordx4 v[16:19], v[22:23], off
	s_ashr_i32 s0, s2, 11
	s_mul_i32 s0, s0, 6
	s_ashr_i32 s1, s0, 31
	s_lshl_b64 s[0:1], s[0:1], 12
	s_add_u32 s0, s7, s0
	s_addc_u32 s1, s35, s1
	v_lshl_add_u64 v[44:45], s[0:1], 0, v[64:65]
	s_mov_b64 s[0:1], 0x1000
	v_lshl_add_u64 v[46:47], v[44:45], 0, s[0:1]
	s_movk_i32 s0, 0x1000
	v_add_co_u32_e32 v40, vcc, s0, v44
	s_add_i32 s2, s2, s6
	s_nop 0
	v_addc_co_u32_e32 v41, vcc, 0, v45, vcc
	flat_load_dwordx4 v[36:39], v[44:45]
	s_nop 0
	flat_load_dwordx4 v[40:43], v[40:41]
	flat_load_dwordx4 v[100:103], v[46:47] offset:1024
	flat_load_dwordx4 v[104:107], v[44:45] offset:1024
	flat_load_dwordx4 v[108:111], v[46:47] offset:2048
	flat_load_dwordx4 v[112:115], v[44:45] offset:2048
	flat_load_dwordx4 v[116:119], v[46:47] offset:3072
	flat_load_dwordx4 v[120:123], v[44:45] offset:3072
	v_lshl_add_u64 v[22:23], v[22:23], 0, s[8:9]
; __device__ __forceinline__ unsigned pk2(float lo, float hi) { f32x2_t v = {lo, hi}; bf16x2_t b = __builtin_convertvector(v, bf16x2_t); return __builtin_bit_cast(unsigned, b); }
; __device__ __forceinline__ void norm_rows(const float* x, const float* g, const float* modl  , int sh_off, int sc_off, bf16_t* h, int gw, int ngw, int lane) {
;     ...
;         f32x4 v[4]; float ss = 0.f;
; #pragma unroll
;         for (int j = 0; j < 4; ++j) { v[j] = xr[64 * j]; ss += (v[j].x * v[j].x + v[j].y * v[j].y) + (v[j].z * v[j].z + v[j].w * v[j].w); }
;         const float rstd = 1.0f / sqrtf(wave_sum(ss) * (1.0f / DM) + NORM_EPS);
;         const float* mb = modl + (size_t)(row >> 11) * 6 * DM;
;         unsigned long long* o8 = (unsigned long long*)(h + (size_t)row * DM) + lane;
; #pragma unroll
;         for (int j = 0; j < 4; ++j) {
;             const f32x4 sc = *((const f32x4*)(mb + sc_off) + lane + 64 * j), sh = *((const f32x4*)(mb + sh_off) + lane + 64 * j);
;             const f32x4 y = v[j] * rstd * gv[j] * (sc + 1.0f) + sh;
;             o8[64 * j] = (unsigned long long)pk2(y.x, y.y) | ((unsigned long long)pk2(y.z, y.w) << 32);
;         }
.Lnr_skip:
	v_mul_f32_e32 v48, v129, v129
	v_mul_f32_e32 v49, v131, v131
	v_mul_f32_e32 v50, v133, v133
	v_mul_f32_e32 v51, v135, v135
	v_mul_f32_e32 v52, v137, v137
	v_mul_f32_e32 v53, v139, v139
	v_fmac_f32_e32 v48, v128, v128
	v_fmac_f32_e32 v49, v130, v130
	v_fmac_f32_e32 v50, v132, v132
	v_fmac_f32_e32 v51, v134, v134
	v_mul_f32_e32 v54, v125, v125
	v_mul_f32_e32 v55, v127, v127
	v_fmac_f32_e32 v52, v136, v136
	v_fmac_f32_e32 v53, v138, v138
	v_add_f32_e32 v48, v48, v49
	v_add_f32_e32 v49, v50, v51
	v_fmac_f32_e32 v54, v124, v124
	v_fmac_f32_e32 v55, v126, v126
	v_add_f32_e32 v50, v52, v53
	v_add_f32_e32 v48, v48, v49
	v_add_f32_e32 v51, v54, v55
	v_add_f32_e32 v48, v48, v50
	v_add_f32_e32 v48, v48, v51
	ds_swizzle_b32 v49, v48 offset:swizzle(SWAP,1)
	s_waitcnt lgkmcnt(0)
	v_pk_add_f32 v[146:147], v[146:147], 1.0 op_sel_hi:[1,0]
	v_pk_add_f32 v[144:145], v[144:145], 1.0 op_sel_hi:[1,0]
	v_add_f32_e32 v48, v48, v49
	ds_swizzle_b32 v49, v48 offset:swizzle(SWAP,2)
	s_waitcnt lgkmcnt(0)
	v_add_f32_e32 v48, v48, v49
	ds_swizzle_b32 v49, v48 offset:swizzle(SWAP,4)
	s_waitcnt lgkmcnt(0)
	v_add_f32_e32 v48, v48, v49
	ds_swizzle_b32 v49, v48 offset:swizzle(SWAP,8)
	s_waitcnt lgkmcnt(0)
	v_add_f32_e32 v48, v48, v49
	ds_swizzle_b32 v49, v48 offset:swizzle(SWAP,16)
	s_waitcnt lgkmcnt(0)
	v_add_f32_e32 v48, v48, v49
	v_mov_b32_e32 v49, v48
	s_nop 1
	v_permlane32_swap_b32_e32 v48, v49
	v_add_f32_e32 v48, v48, v49
	v_fmamk_f32 v48, v48, 0x3a800000, v242
	v_mul_f32_e32 v49, 0x4f800000, v48
	v_cmp_gt_f32_e32 vcc, s3, v48
	s_nop 1
	v_cndmask_b32_e32 v48, v48, v49, vcc
	v_sqrt_f32_e32 v49, v48
	s_nop 0
	v_add_u32_e32 v50, -1, v49
	v_add_u32_e32 v51, 1, v49
	v_fma_f32 v52, -v50, v49, v48
	v_fma_f32 v53, -v51, v49, v48
	v_cmp_ge_f32_e64 s[0:1], 0, v52
	s_nop 1
	v_cndmask_b32_e64 v49, v49, v50, s[0:1]
	v_cmp_lt_f32_e64 s[0:1], 0, v53
	s_nop 1
	v_cndmask_b32_e64 v49, v49, v51, s[0:1]
	v_mul_f32_e32 v50, 0x37800000, v49
	v_cndmask_b32_e32 v49, v49, v50, vcc
	v_cmp_class_f32_e32 vcc, v48, v245
	s_nop 1
	v_cndmask_b32_e32 v48, v49, v48, vcc
	v_div_scale_f32 v49, s[0:1], v48, v48, 1.0
	v_rcp_f32_e32 v51, v49
	v_div_scale_f32 v50, vcc, 1.0, v48, 1.0
	v_fma_f32 v52, -v49, v51, 1.0
	v_fmac_f32_e32 v51, v52, v51
	v_mul_f32_e32 v52, v50, v51
	v_fma_f32 v53, -v49, v52, v50
	v_fmac_f32_e32 v52, v53, v51
	v_fma_f32 v49, -v49, v52, v50
	v_div_fmas_f32 v49, v49, v51, v52
	v_div_fixup_f32 v48, v49, v48, 1.0
	v_pk_mul_f32 v[130:131], v[130:131], v[48:49] op_sel_hi:[1,0]
	v_pk_mul_f32 v[128:129], v[128:129], v[48:49] op_sel_hi:[1,0]
	v_pk_mul_f32 v[130:131], v[2:3], v[130:131]
	v_pk_mul_f32 v[128:129], v[0:1], v[128:129]
	v_pk_fma_f32 v[130:131], v[146:147], v[130:131], v[142:143]
	v_pk_fma_f32 v[128:129], v[144:145], v[128:129], v[140:141]
	v_pk_mul_f32 v[134:135], v[134:135], v[48:49] op_sel_hi:[1,0]
	v_cvt_pk_bf16_f32 v128, v128, v129
	v_cvt_pk_bf16_f32 v129, v130, v131
	flat_store_dwordx2 v[20:21], v[128:129]
	s_nop 0
	v_pk_mul_f32 v[132:133], v[132:133], v[48:49] op_sel_hi:[1,0]
	v_pk_mul_f32 v[134:135], v[6:7], v[134:135]
	v_pk_mul_f32 v[132:133], v[4:5], v[132:133]
	v_pk_mul_f32 v[138:139], v[138:139], v[48:49] op_sel_hi:[1,0]
	v_pk_mul_f32 v[136:137], v[136:137], v[48:49] op_sel_hi:[1,0]
	v_pk_mul_f32 v[138:139], v[10:11], v[138:139]
	v_pk_mul_f32 v[136:137], v[8:9], v[136:137]
	v_pk_mul_f32 v[126:127], v[126:127], v[48:49] op_sel_hi:[1,0]
	v_pk_mul_f32 v[124:125], v[124:125], v[48:49] op_sel_hi:[1,0]
	v_pk_mul_f32 v[126:127], v[14:15], v[126:127]
	v_pk_mul_f32 v[124:125], v[12:13], v[124:125]
	v_pk_add_f32 v[130:131], v[150:151], 1.0 op_sel_hi:[1,0]
	v_pk_add_f32 v[128:129], v[148:149], 1.0 op_sel_hi:[1,0]
	v_pk_fma_f32 v[130:131], v[130:131], v[134:135], v[154:155]
	v_pk_fma_f32 v[128:129], v[128:129], v[132:133], v[152:153]
	s_nop 0
	v_cvt_pk_bf16_f32 v128, v128, v129
	v_cvt_pk_bf16_f32 v129, v130, v131
	flat_store_dwordx2 v[20:21], v[128:129] offset:512
	s_nop 0
	v_pk_add_f32 v[130:131], v[158:159], 1.0 op_sel_hi:[1,0]
	v_pk_add_f32 v[128:129], v[156:157], 1.0 op_sel_hi:[1,0]
	v_pk_fma_f32 v[130:131], v[130:131], v[138:139], v[162:163]
	v_pk_fma_f32 v[128:129], v[128:129], v[136:137], v[160:161]
	s_nop 0
	v_cvt_pk_bf16_f32 v128, v128, v129
	v_cvt_pk_bf16_f32 v129, v130, v131
	flat_store_dwordx2 v[20:21], v[128:129] offset:1024
	s_nop 0
	v_pk_add_f32 v[130:131], v[166:167], 1.0 op_sel_hi:[1,0]
	v_pk_add_f32 v[128:129], v[164:165], 1.0 op_sel_hi:[1,0]
	v_pk_fma_f32 v[126:127], v[126:127], v[130:131], v[170:171]
	v_pk_fma_f32 v[124:125], v[124:125], v[128:129], v[168:169]
	s_nop 0
	v_cvt_pk_bf16_f32 v124, v124, v125
	v_cvt_pk_bf16_f32 v125, v126, v127
	flat_store_dwordx2 v[20:21], v[124:125] offset:1536
	v_lshl_add_u64 v[20:21], v[20:21], 0, s[4:5]
	s_cmp_eq_u32 s98, 0
	s_cbranch_scc1 .LBB0_691
